# w_out + first 432 w_up transpose items moved to the phase-2 queue tail: phase 0 has exactly 6 static rounds
# baseline (speedup 1.0000x reference)
.LBB0_33:
	s_or_b64 exec, exec, s[4:5]
	v_writelane_b32 v252, s60, 8
	s_cmpk_gt_i32 s2, 0xe2f
	v_and_b32_e32 v161, 63, v162
	v_writelane_b32 v252, s61, 9
	v_writelane_b32 v252, s62, 10
	v_writelane_b32 v252, s63, 11
	v_writelane_b32 v252, s64, 12
	v_writelane_b32 v252, s65, 13
	v_writelane_b32 v252, s66, 14
	v_writelane_b32 v252, s67, 15
	v_writelane_b32 v252, s68, 16
	v_writelane_b32 v252, s69, 17
	v_writelane_b32 v252, s70, 18
	v_writelane_b32 v252, s71, 19
	v_writelane_b32 v252, s72, 20
	v_writelane_b32 v252, s73, 21
	v_lshrrev_b32_e32 v160, 6, v162
	v_lshrrev_b32_e32 v228, 5, v162
	v_lshlrev_b32_e32 v229, 2, v162
	v_mbcnt_lo_u32_b32 v230, -1, 0
	v_writelane_b32 v252, s74, 22
	v_writelane_b32 v252, s75, 23
	s_cbranch_scc1 .LBB0_59
	s_load_dword s11, s[0:1], 0x1b8
	s_waitcnt lgkmcnt(0)
	s_load_dwordx16 s[12:27], s[0:1], 0xc0
	v_lshlrev_b32_e32 v1, 2, v162
	v_mov_b32_e32 v167, 0
	v_and_b32_e32 v166, 0x7c, v1
	s_movk_i32 s4, 0x84
	s_waitcnt lgkmcnt(0)
	v_lshl_add_u64 v[170:171], s[16:17], 0, v[166:167]
	s_load_dwordx8 s[16:23], s[0:1], 0x180
	v_lshl_add_u64 v[174:175], s[12:13], 0, v[166:167]
	v_lshlrev_b32_e32 v0, 2, v161
	v_lshlrev_b32_e32 v168, 4, v161
	v_mul_u32_u24_e32 v1, 0x74, v161
	s_waitcnt lgkmcnt(0)
	s_mov_b64 s[58:59], s[22:23]
	s_mov_b64 s[56:57], s[20:21]
	s_mov_b64 s[54:55], s[18:19]
	s_mov_b64 s[52:53], s[16:17]
	s_load_dwordx16 s[12:27], s[0:1], 0x80
	v_lshlrev_b32_e32 v2, 2, v160
	v_mad_u32_u24 v231, v228, s4, v166
	s_lshl_b32 s4, s2, 3
	v_mbcnt_hi_u32_b32 v232, -1, v230
	s_waitcnt lgkmcnt(0)
	v_lshl_add_u64 v[178:179], s[24:25], 0, v[166:167]
	v_lshl_add_u64 v[182:183], s[14:15], 0, v[166:167]
	s_load_dwordx16 s[12:27], s[0:1], 0x140
	v_add3_u32 v163, v168, v1, v2
	v_lshlrev_b32_e32 v2, 1, v161
	v_mov_b32_e32 v3, v167
	v_lshl_add_u64 v[186:187], s[36:37], 0, v[166:167]
	v_mov_b32_e32 v169, v167
	v_lshlrev_b32_e32 v166, 3, v161
	s_waitcnt lgkmcnt(0)
	s_add_i32 s12, s4, 0x7ffff000
	s_lshl_b32 s4, s2, 4
	v_lshlrev_b32_e32 v194, 2, v0
	v_and_b32_e32 v0, 64, v232
	v_lshl_add_u64 v[172:173], s[56:57], 0, v[2:3]
	v_lshl_add_u64 v[176:177], s[54:55], 0, v[2:3]
	v_lshl_add_u64 v[180:181], s[52:53], 0, v[2:3]
	v_lshl_add_u64 v[184:185], s[26:27], 0, v[2:3]
	v_lshl_add_u64 v[188:189], s[24:25], 0, v[2:3]
	v_lshl_add_u64 v[190:191], s[74:75], 0, v[168:169]
	v_readfirstlane_b32 s98, v160
	s_nop 3
	s_lshl_b32 s98, s98, 12
	s_add_u32 s98, s98, 0xb000
	s_mov_b32 m0, s98
	v_lshl_add_u32 v250, v161, 4, s98
	global_load_lds_dwordx4 v[190:191], off
	global_load_lds_dwordx4 v[190:191], off offset:1024
	global_load_lds_dwordx4 v[190:191], off offset:2048
	global_load_lds_dwordx4 v[190:191], off offset:3072
	v_lshl_add_u64 v[192:193], s[58:59], 0, v[166:167]
	s_add_i32 s13, s4, 0x7fffec00
	v_mov_b32_e32 v169, 0x358637bd
	v_add_u32_e32 v233, 64, v0
	v_xor_b32_e32 v234, 32, v232
	v_xor_b32_e32 v235, 16, v232
	v_xor_b32_e32 v236, 8, v232
	v_xor_b32_e32 v237, 4, v232
	v_xor_b32_e32 v238, 2, v232
	v_xor_b32_e32 v239, 1, v232
	s_lshl_b32 s14, s11, 3
	s_lshl_b32 s15, s11, 8
	s_lshl_b32 s16, s11, 4
	s_movk_i32 s17, 0x4000
	s_mov_b32 s18, 0x800000
	s_mov_b32 s19, 0x10000
	s_mov_b32 s20, 0x28000
	s_mov_b32 s21, 0x50000
	s_mov_b32 s22, 0x58000
	s_mov_b32 s23, 0x78000
	s_mov_b32 s24, 0xa0000
	s_mov_b32 s25, 0xb0000
	s_mov_b32 s26, 0xc8000
	s_mov_b32 s27, 0xf0000
	s_mov_b32 s33, s2
	s_mov_b32 s7, 0
	v_cmp_eq_u32_e64 s[4:5], 0, v161
	s_mov_b32 s32, 0
	s_cmpk_lt_u32 s33, 0x180
	s_cbranch_scc1 .Lp0_noshift
	s_addk_i32 s33, 0x230
	s_add_i32 s12, s12, 0x1180
	s_add_i32 s10, s10, 0x23000
	s_add_i32 s13, s13, 0x2300
	s_mov_b32 s32, 1

.LBB0_35:
	s_add_i32 s33, s33, s11
	s_add_i32 s12, s12, s14
	s_add_i32 s10, s10, s15
	s_add_i32 s13, s13, s16
	s_cmp_eq_u32 s32, 0
	s_cbranch_scc0 .Lp0_shifted
	s_addk_i32 s33, 0x230
	s_add_i32 s12, s12, 0x1180
	s_add_i32 s10, s10, 0x23000
	s_add_i32 s13, s13, 0x2300
	s_mov_b32 s32, 1

.LBB0_196:
	s_or_b64 exec, exec, s[0:1]
	s_waitcnt lgkmcnt(0)
	s_barrier
	ds_read_b32 v0, v194
	s_movk_i32 s0, 0x7af
	s_waitcnt lgkmcnt(0)
	v_cmp_lt_i32_e32 vcc, s0, v0
	v_readfirstlane_b32 s36, v0
	s_mov_b64 s[0:1], -1
	s_cbranch_vccnz .LBB0_191
	s_cmpk_gt_i32 s36, 0xff
	s_cbranch_scc0 .LBB0_316
	s_cmpk_gt_u32 s36, 0x4ff
	s_cbranch_scc0 .LBB0_212
	s_cmpk_gt_u32 s36, 0x57f
	s_cbranch_scc1 .Lp2_tr
	v_readlane_b32 s12, v252, 30
	v_readlane_b32 s13, v252, 31
	s_barrier
	s_and_saveexec_b64 s[0:1], s[12:13]
	v_readlane_b32 s68, v251, 8
	v_readlane_b32 s78, v251, 18
	v_readlane_b32 s79, v251, 19
	v_readlane_b32 s69, v251, 9
	v_readlane_b32 s70, v251, 10
	v_readlane_b32 s71, v251, 11
	v_readlane_b32 s72, v251, 12
	v_readlane_b32 s73, v251, 13
	v_readlane_b32 s74, v251, 14
	v_readlane_b32 s75, v251, 15
	v_readlane_b32 s76, v251, 16
	v_readlane_b32 s77, v251, 17
	v_readlane_b32 s80, v251, 20
	v_readlane_b32 s81, v251, 21
	v_readlane_b32 s82, v251, 22
	v_readlane_b32 s83, v251, 23
	s_cbranch_execz .LBB0_202
	s_mov_b64 s[14:15], 0
	v_mov_b32_e32 v2, v229
	v_mov_b32_e32 v3, v103

.Lp2_tr:
	s_sub_u32 s12, s36, 0x580
	s_cmp_lt_u32 s12, 0x80
	s_cbranch_scc1 .Lp2_tr_out
	s_sub_u32 s12, s12, 0x80
	s_lshr_b32 s13, s12, 2
	s_lshl_b32 s13, s13, 5
	s_and_b32 s14, s12, 3
	s_lshl_b32 s14, s14, 8
	s_lshr_b32 s15, s13, 7
	s_lshl_b32 s15, s15, 6
	s_bfe_u32 s18, s13, 0x10006
	s_lshl_b32 s18, s18, 5
	s_add_u32 s15, s15, s18
	s_bfe_u32 s18, s13, 0x10005
	s_mul_i32 s18, s18, 0xb00
	s_add_u32 s15, s15, s18
	s_mov_b32 s16, 0x5800
	s_mov_b32 s17, 0x800
	v_readlane_b32 s70, v251, 40
	v_readlane_b32 s71, v251, 41
	v_readlane_b32 s72, v251, 2
	v_readlane_b32 s73, v251, 3
	s_branch .Lp2_tr_go
.Lp2_tr_out:
	s_lshr_b32 s13, s12, 2
	s_lshl_b32 s13, s13, 5
	s_and_b32 s14, s12, 3
	s_lshl_b32 s14, s14, 8
	s_mov_b32 s15, s13
	s_mov_b32 s16, 0x1000
	s_mov_b32 s17, 0x800
	v_readlane_b32 s70, v251, 36
	v_readlane_b32 s71, v251, 37
	v_readlane_b32 s72, v251, 0
	v_readlane_b32 s73, v251, 1
.Lp2_tr_go:
	s_mul_i32 s18, s14, s16
	s_lshl_b32 s19, s15, 2
	s_add_u32 s18, s18, s19
	s_add_u32 s70, s70, s18
	s_addc_u32 s71, s71, 0
	s_mul_i32 s18, s13, s17
	s_lshl_b32 s19, s14, 1
	s_add_u32 s18, s18, s19
	s_add_u32 s72, s72, s18
	s_addc_u32 s73, s73, 0
	s_lshl_b32 s74, s16, 3
	s_lshl_b32 s75, s17, 2
	v_and_b32_e32 v176, 31, v162
	v_lshrrev_b32_e32 v177, 5, v162
	v_lshlrev_b32_e32 v178, 2, v176
	v_mad_u32_u24 v178, v177, s16, v178
	v_mul_u32_u24_e32 v179, 33, v177
	v_add_lshl_u32 v179, v179, v176, 2
	v_and_b32_e32 v180, 63, v162
	v_lshrrev_b32_e32 v181, 6, v162
	v_mul_u32_u24_e32 v182, 33, v180
	v_add_lshl_u32 v182, v182, v181, 2
	v_lshlrev_b32_e32 v183, 1, v180
	v_mad_u32_u24 v183, v181, s17, v183
	s_waitcnt lgkmcnt(0)
	s_barrier
	s_mov_b64 s[76:77], s[70:71]
	global_load_dword v40, v178, s[76:77]
	s_add_u32 s76, s76, s74
	s_addc_u32 s77, s77, 0
	global_load_dword v41, v178, s[76:77]
	s_add_u32 s76, s76, s74
	s_addc_u32 s77, s77, 0
	global_load_dword v42, v178, s[76:77]
	s_add_u32 s76, s76, s74
	s_addc_u32 s77, s77, 0
	global_load_dword v43, v178, s[76:77]
	s_add_u32 s76, s76, s74
	s_addc_u32 s77, s77, 0
	global_load_dword v44, v178, s[76:77]
	s_add_u32 s76, s76, s74
	s_addc_u32 s77, s77, 0
	global_load_dword v45, v178, s[76:77]
	s_add_u32 s76, s76, s74
	s_addc_u32 s77, s77, 0
	global_load_dword v46, v178, s[76:77]
	s_add_u32 s76, s76, s74
	s_addc_u32 s77, s77, 0
	global_load_dword v47, v178, s[76:77]
	s_add_u32 s76, s76, s74
	s_addc_u32 s77, s77, 0
	global_load_dword v48, v178, s[76:77]
	s_add_u32 s76, s76, s74
	s_addc_u32 s77, s77, 0
	global_load_dword v49, v178, s[76:77]
	s_add_u32 s76, s76, s74
	s_addc_u32 s77, s77, 0
	global_load_dword v50, v178, s[76:77]
	s_add_u32 s76, s76, s74
	s_addc_u32 s77, s77, 0
	global_load_dword v51, v178, s[76:77]
	s_add_u32 s76, s76, s74
	s_addc_u32 s77, s77, 0
	global_load_dword v52, v178, s[76:77]
	s_add_u32 s76, s76, s74
	s_addc_u32 s77, s77, 0
	global_load_dword v53, v178, s[76:77]
	s_add_u32 s76, s76, s74
	s_addc_u32 s77, s77, 0
	global_load_dword v54, v178, s[76:77]
	s_add_u32 s76, s76, s74
	s_addc_u32 s77, s77, 0
	global_load_dword v55, v178, s[76:77]
	s_add_u32 s76, s76, s74
	s_addc_u32 s77, s77, 0
	global_load_dword v56, v178, s[76:77]
	s_add_u32 s76, s76, s74
	s_addc_u32 s77, s77, 0
	global_load_dword v57, v178, s[76:77]
	s_add_u32 s76, s76, s74
	s_addc_u32 s77, s77, 0
	global_load_dword v58, v178, s[76:77]
	s_add_u32 s76, s76, s74
	s_addc_u32 s77, s77, 0
	global_load_dword v59, v178, s[76:77]
	s_add_u32 s76, s76, s74
	s_addc_u32 s77, s77, 0
	global_load_dword v60, v178, s[76:77]
	s_add_u32 s76, s76, s74
	s_addc_u32 s77, s77, 0
	global_load_dword v61, v178, s[76:77]
	s_add_u32 s76, s76, s74
	s_addc_u32 s77, s77, 0
	global_load_dword v62, v178, s[76:77]
	s_add_u32 s76, s76, s74
	s_addc_u32 s77, s77, 0
	global_load_dword v63, v178, s[76:77]
	s_add_u32 s76, s76, s74
	s_addc_u32 s77, s77, 0
	global_load_dword v64, v178, s[76:77]
	s_add_u32 s76, s76, s74
	s_addc_u32 s77, s77, 0
	global_load_dword v65, v178, s[76:77]
	s_add_u32 s76, s76, s74
	s_addc_u32 s77, s77, 0
	global_load_dword v66, v178, s[76:77]
	s_add_u32 s76, s76, s74
	s_addc_u32 s77, s77, 0
	global_load_dword v124, v178, s[76:77]
	s_add_u32 s76, s76, s74
	s_addc_u32 s77, s77, 0
	global_load_dword v125, v178, s[76:77]
	s_add_u32 s76, s76, s74
	s_addc_u32 s77, s77, 0
	global_load_dword v126, v178, s[76:77]
	s_add_u32 s76, s76, s74
	s_addc_u32 s77, s77, 0
	global_load_dword v127, v178, s[76:77]
	s_add_u32 s76, s76, s74
	s_addc_u32 s77, s77, 0
	global_load_dword v128, v178, s[76:77]
	s_waitcnt vmcnt(31)
	ds_write_b32 v179, v40 offset:0
	s_waitcnt vmcnt(30)
	ds_write_b32 v179, v41 offset:1056
	s_waitcnt vmcnt(29)
	ds_write_b32 v179, v42 offset:2112
	s_waitcnt vmcnt(28)
	ds_write_b32 v179, v43 offset:3168
	s_waitcnt vmcnt(27)
	ds_write_b32 v179, v44 offset:4224
	s_waitcnt vmcnt(26)
	ds_write_b32 v179, v45 offset:5280
	s_waitcnt vmcnt(25)
	ds_write_b32 v179, v46 offset:6336
	s_waitcnt vmcnt(24)
	ds_write_b32 v179, v47 offset:7392
	s_waitcnt lgkmcnt(0)
	s_barrier
	ds_read_b32 v168, v182 offset:0
	ds_read_b32 v169, v182 offset:16
	ds_read_b32 v170, v182 offset:32
	ds_read_b32 v171, v182 offset:48
	ds_read_b32 v172, v182 offset:64
	ds_read_b32 v173, v182 offset:80
	ds_read_b32 v174, v182 offset:96
	ds_read_b32 v175, v182 offset:112
	s_mov_b64 s[78:79], s[72:73]
	s_waitcnt lgkmcnt(7)
	v_cvt_pk_bf16_f32 v168, v168, v168
	global_store_short v183, v168, s[78:79] offset:0
	s_add_u32 s78, s78, s75
	s_addc_u32 s79, s79, 0
	s_waitcnt lgkmcnt(6)
	v_cvt_pk_bf16_f32 v169, v169, v169
	global_store_short v183, v169, s[78:79] offset:0
	s_add_u32 s78, s78, s75
	s_addc_u32 s79, s79, 0
	s_waitcnt lgkmcnt(5)
	v_cvt_pk_bf16_f32 v170, v170, v170
	global_store_short v183, v170, s[78:79] offset:0
	s_add_u32 s78, s78, s75
	s_addc_u32 s79, s79, 0
	s_waitcnt lgkmcnt(4)
	v_cvt_pk_bf16_f32 v171, v171, v171
	global_store_short v183, v171, s[78:79] offset:0
	s_add_u32 s78, s78, s75
	s_addc_u32 s79, s79, 0
	s_waitcnt lgkmcnt(3)
	v_cvt_pk_bf16_f32 v172, v172, v172
	global_store_short v183, v172, s[78:79] offset:0
	s_add_u32 s78, s78, s75
	s_addc_u32 s79, s79, 0
	s_waitcnt lgkmcnt(2)
	v_cvt_pk_bf16_f32 v173, v173, v173
	global_store_short v183, v173, s[78:79] offset:0
	s_add_u32 s78, s78, s75
	s_addc_u32 s79, s79, 0
	s_waitcnt lgkmcnt(1)
	v_cvt_pk_bf16_f32 v174, v174, v174
	global_store_short v183, v174, s[78:79] offset:0
	s_add_u32 s78, s78, s75
	s_addc_u32 s79, s79, 0
	s_waitcnt lgkmcnt(0)
	v_cvt_pk_bf16_f32 v175, v175, v175
	global_store_short v183, v175, s[78:79] offset:0
	s_barrier
	s_waitcnt vmcnt(31)
	ds_write_b32 v179, v48 offset:0
	s_waitcnt vmcnt(30)
	ds_write_b32 v179, v49 offset:1056
	s_waitcnt vmcnt(29)
	ds_write_b32 v179, v50 offset:2112
	s_waitcnt vmcnt(28)
	ds_write_b32 v179, v51 offset:3168
	s_waitcnt vmcnt(27)
	ds_write_b32 v179, v52 offset:4224
	s_waitcnt vmcnt(26)
	ds_write_b32 v179, v53 offset:5280
	s_waitcnt vmcnt(25)
	ds_write_b32 v179, v54 offset:6336
	s_waitcnt vmcnt(24)
	ds_write_b32 v179, v55 offset:7392
	s_waitcnt lgkmcnt(0)
	s_barrier
	ds_read_b32 v168, v182 offset:0
	ds_read_b32 v169, v182 offset:16
	ds_read_b32 v170, v182 offset:32
	ds_read_b32 v171, v182 offset:48
	ds_read_b32 v172, v182 offset:64
	ds_read_b32 v173, v182 offset:80
	ds_read_b32 v174, v182 offset:96
	ds_read_b32 v175, v182 offset:112
	s_mov_b64 s[78:79], s[72:73]
	s_waitcnt lgkmcnt(7)
	v_cvt_pk_bf16_f32 v168, v168, v168
	global_store_short v183, v168, s[78:79] offset:128
	s_add_u32 s78, s78, s75
	s_addc_u32 s79, s79, 0
	s_waitcnt lgkmcnt(6)
	v_cvt_pk_bf16_f32 v169, v169, v169
	global_store_short v183, v169, s[78:79] offset:128
	s_add_u32 s78, s78, s75
	s_addc_u32 s79, s79, 0
	s_waitcnt lgkmcnt(5)
	v_cvt_pk_bf16_f32 v170, v170, v170
	global_store_short v183, v170, s[78:79] offset:128
	s_add_u32 s78, s78, s75
	s_addc_u32 s79, s79, 0
	s_waitcnt lgkmcnt(4)
	v_cvt_pk_bf16_f32 v171, v171, v171
	global_store_short v183, v171, s[78:79] offset:128
	s_add_u32 s78, s78, s75
	s_addc_u32 s79, s79, 0
	s_waitcnt lgkmcnt(3)
	v_cvt_pk_bf16_f32 v172, v172, v172
	global_store_short v183, v172, s[78:79] offset:128
	s_add_u32 s78, s78, s75
	s_addc_u32 s79, s79, 0
	s_waitcnt lgkmcnt(2)
	v_cvt_pk_bf16_f32 v173, v173, v173
	global_store_short v183, v173, s[78:79] offset:128
	s_add_u32 s78, s78, s75
	s_addc_u32 s79, s79, 0
	s_waitcnt lgkmcnt(1)
	v_cvt_pk_bf16_f32 v174, v174, v174
	global_store_short v183, v174, s[78:79] offset:128
	s_add_u32 s78, s78, s75
	s_addc_u32 s79, s79, 0
	s_waitcnt lgkmcnt(0)
	v_cvt_pk_bf16_f32 v175, v175, v175
	global_store_short v183, v175, s[78:79] offset:128
	s_barrier
	s_waitcnt vmcnt(31)
	ds_write_b32 v179, v56 offset:0
	s_waitcnt vmcnt(30)
	ds_write_b32 v179, v57 offset:1056
	s_waitcnt vmcnt(29)
	ds_write_b32 v179, v58 offset:2112
	s_waitcnt vmcnt(28)
	ds_write_b32 v179, v59 offset:3168
	s_waitcnt vmcnt(27)
	ds_write_b32 v179, v60 offset:4224
	s_waitcnt vmcnt(26)
	ds_write_b32 v179, v61 offset:5280
	s_waitcnt vmcnt(25)
	ds_write_b32 v179, v62 offset:6336
	s_waitcnt vmcnt(24)
	ds_write_b32 v179, v63 offset:7392
	s_waitcnt lgkmcnt(0)
	s_barrier
	ds_read_b32 v168, v182 offset:0
	ds_read_b32 v169, v182 offset:16
	ds_read_b32 v170, v182 offset:32
	ds_read_b32 v171, v182 offset:48
	ds_read_b32 v172, v182 offset:64
	ds_read_b32 v173, v182 offset:80
	ds_read_b32 v174, v182 offset:96
	ds_read_b32 v175, v182 offset:112
	s_mov_b64 s[78:79], s[72:73]
	s_waitcnt lgkmcnt(7)
	v_cvt_pk_bf16_f32 v168, v168, v168
	global_store_short v183, v168, s[78:79] offset:256
	s_add_u32 s78, s78, s75
	s_addc_u32 s79, s79, 0
	s_waitcnt lgkmcnt(6)
	v_cvt_pk_bf16_f32 v169, v169, v169
	global_store_short v183, v169, s[78:79] offset:256
	s_add_u32 s78, s78, s75
	s_addc_u32 s79, s79, 0
	s_waitcnt lgkmcnt(5)
	v_cvt_pk_bf16_f32 v170, v170, v170
	global_store_short v183, v170, s[78:79] offset:256
	s_add_u32 s78, s78, s75
	s_addc_u32 s79, s79, 0
	s_waitcnt lgkmcnt(4)
	v_cvt_pk_bf16_f32 v171, v171, v171
	global_store_short v183, v171, s[78:79] offset:256
	s_add_u32 s78, s78, s75
	s_addc_u32 s79, s79, 0
	s_waitcnt lgkmcnt(3)
	v_cvt_pk_bf16_f32 v172, v172, v172
	global_store_short v183, v172, s[78:79] offset:256
	s_add_u32 s78, s78, s75
	s_addc_u32 s79, s79, 0
	s_waitcnt lgkmcnt(2)
	v_cvt_pk_bf16_f32 v173, v173, v173
	global_store_short v183, v173, s[78:79] offset:256
	s_add_u32 s78, s78, s75
	s_addc_u32 s79, s79, 0
	s_waitcnt lgkmcnt(1)
	v_cvt_pk_bf16_f32 v174, v174, v174
	global_store_short v183, v174, s[78:79] offset:256
	s_add_u32 s78, s78, s75
	s_addc_u32 s79, s79, 0
	s_waitcnt lgkmcnt(0)
	v_cvt_pk_bf16_f32 v175, v175, v175
	global_store_short v183, v175, s[78:79] offset:256
	s_barrier
	s_waitcnt vmcnt(31)
	ds_write_b32 v179, v64 offset:0
	s_waitcnt vmcnt(30)
	ds_write_b32 v179, v65 offset:1056
	s_waitcnt vmcnt(29)
	ds_write_b32 v179, v66 offset:2112
	s_waitcnt vmcnt(28)
	ds_write_b32 v179, v124 offset:3168
	s_waitcnt vmcnt(27)
	ds_write_b32 v179, v125 offset:4224
	s_waitcnt vmcnt(26)
	ds_write_b32 v179, v126 offset:5280
	s_waitcnt vmcnt(25)
	ds_write_b32 v179, v127 offset:6336
	s_waitcnt vmcnt(24)
	ds_write_b32 v179, v128 offset:7392
	s_waitcnt lgkmcnt(0)
	s_barrier
	ds_read_b32 v168, v182 offset:0
	ds_read_b32 v169, v182 offset:16
	ds_read_b32 v170, v182 offset:32
	ds_read_b32 v171, v182 offset:48
	ds_read_b32 v172, v182 offset:64
	ds_read_b32 v173, v182 offset:80
	ds_read_b32 v174, v182 offset:96
	ds_read_b32 v175, v182 offset:112
	s_mov_b64 s[78:79], s[72:73]
	s_waitcnt lgkmcnt(7)
	v_cvt_pk_bf16_f32 v168, v168, v168
	global_store_short v183, v168, s[78:79] offset:384
	s_add_u32 s78, s78, s75
	s_addc_u32 s79, s79, 0
	s_waitcnt lgkmcnt(6)
	v_cvt_pk_bf16_f32 v169, v169, v169
	global_store_short v183, v169, s[78:79] offset:384
	s_add_u32 s78, s78, s75
	s_addc_u32 s79, s79, 0
	s_waitcnt lgkmcnt(5)
	v_cvt_pk_bf16_f32 v170, v170, v170
	global_store_short v183, v170, s[78:79] offset:384
	s_add_u32 s78, s78, s75
	s_addc_u32 s79, s79, 0
	s_waitcnt lgkmcnt(4)
	v_cvt_pk_bf16_f32 v171, v171, v171
	global_store_short v183, v171, s[78:79] offset:384
	s_add_u32 s78, s78, s75
	s_addc_u32 s79, s79, 0
	s_waitcnt lgkmcnt(3)
	v_cvt_pk_bf16_f32 v172, v172, v172
	global_store_short v183, v172, s[78:79] offset:384
	s_add_u32 s78, s78, s75
	s_addc_u32 s79, s79, 0
	s_waitcnt lgkmcnt(2)
	v_cvt_pk_bf16_f32 v173, v173, v173
	global_store_short v183, v173, s[78:79] offset:384
	s_add_u32 s78, s78, s75
	s_addc_u32 s79, s79, 0
	s_waitcnt lgkmcnt(1)
	v_cvt_pk_bf16_f32 v174, v174, v174
	global_store_short v183, v174, s[78:79] offset:384
	s_add_u32 s78, s78, s75
	s_addc_u32 s79, s79, 0
	s_waitcnt lgkmcnt(0)
	v_cvt_pk_bf16_f32 v175, v175, v175
	global_store_short v183, v175, s[78:79] offset:384
	s_barrier
	s_branch .LBB0_190
